# v75 + FFN1: leading half's extra barrier moved from before its epilogue to after the epilogue's 3rd store group (first part of its epilogue overlaps the partner half's last MFMA block)
# baseline (speedup 1.0000x reference)
; __device__ __forceinline__ u32x4 pack8(const float (&o)[8]) { u32x4 r; r.x = pk2(o[0], o[1]); r.y = pk2(o[2], o[3]); r.z = pk2(o[4], o[5]); r.w = pk2(o[6], o[7]); return r; }
; __device__ __forceinline__ float silu_f(float v) { return v * __builtin_amdgcn_rcpf(1.f + __expf(-v)); }
; #define PG8_BAR __builtin_amdgcn_s_barrier()
; template <class Epi, bool ALIGN_EPI = PG8_ALIGN, bool SP2 = PG8_SP2>
; __device__ __forceinline__ void gemm_phase(LAS uchar* lds, const Gemm g, const StaticOrder& S, const Epi& E) {
;     ...
;         if constexpr (ALIGN_EPI) { if (wr == 0) PG8_BAR; }
;     __device__ __forceinline__ void operator()(const f32x4 (&acc)[2][2][4][2], const pg8::Unit& u, int wr, int wc, int fr, int fq, int) const {
;         const int row0 = u.pm * 256 + wr * 64 + fr, col0 = u.pn * 128 + wc * 32 + 8 * fq;
; #pragma unroll
;         for (int ai = 0; ai < 2; ++ai)
; #pragma unroll
;             for (int m = 0; m < 4; ++m) { bf16_t* rowp = O + (size_t)(row0 + ai * 128 + m * 16) * DFF + col0;
;                 float r[8];
; #pragma unroll
;                 for (int n = 0; n < 2; ++n)
; #pragma unroll
;                     for (int i = 0; i < 4; ++i) { const float gt = acc[ai][0][m][n][i], up = acc[ai][1][m][n][i]; r[n * 4 + i] = silu_f(gt) * up; }
;                 *(u32x4*)rowp = pack8(r); }
.LBB0_1053:
	v_lshl_or_b32 v166, s35, 7, v162
	v_lshl_add_u32 v164, s34, 8, v1
	v_mov_b32_e32 v252, 0xbfb8aa3b
	v_mov_b32_e32 v253, 0xbfb8aa3b
	v_ashrrev_i32_e32 v167, 31, v166
	v_mov_b64_e32 v[160:161], s[90:91]
	v_mov_b32_e32 v250, 1.0
	v_mov_b32_e32 v251, 1.0
	v_lshlrev_b64 v[166:167], 1, v[166:167]
	s_and_b64 vcc, exec, s[4:5]
	v_lshl_add_u64 v[160:161], v[160:161], 0, v[166:167]
	v_mad_i64_i32 v[200:201], s[12:13], v164, s80, v[160:161]
	v_pk_mul_f32 v[122:123], v[126:127], v[122:123]
	v_pk_mul_f32 v[124:125], v[128:129], v[124:125]
	v_pk_mul_f32 v[114:115], v[118:119], v[114:115]
	v_pk_mul_f32 v[116:117], v[120:121], v[116:117]
	v_pk_mul_f32 v[126:127], v[126:127], v[252:253]
	v_pk_mul_f32 v[128:129], v[128:129], v[252:253]
	v_pk_mul_f32 v[118:119], v[118:119], v[252:253]
	v_pk_mul_f32 v[120:121], v[120:121], v[252:253]
	v_exp_f32_e32 v126, v126
	v_exp_f32_e32 v127, v127
	v_exp_f32_e32 v128, v128
	v_exp_f32_e32 v129, v129
	v_exp_f32_e32 v118, v118
	v_exp_f32_e32 v119, v119
	v_exp_f32_e32 v120, v120
	v_exp_f32_e32 v121, v121
	v_pk_add_f32 v[126:127], v[126:127], v[250:251]
	v_pk_add_f32 v[128:129], v[128:129], v[250:251]
	v_pk_add_f32 v[118:119], v[118:119], v[250:251]
	v_pk_add_f32 v[120:121], v[120:121], v[250:251]
	v_rcp_f32_e32 v126, v126
	v_rcp_f32_e32 v127, v127
	v_rcp_f32_e32 v128, v128
	v_rcp_f32_e32 v129, v129
	v_rcp_f32_e32 v118, v118
	v_rcp_f32_e32 v119, v119
	v_rcp_f32_e32 v120, v120
	v_rcp_f32_e32 v121, v121
	v_pk_mul_f32 v[122:123], v[122:123], v[126:127]
	v_pk_mul_f32 v[124:125], v[124:125], v[128:129]
	v_pk_mul_f32 v[114:115], v[114:115], v[118:119]
	v_pk_mul_f32 v[116:117], v[116:117], v[120:121]
	v_cvt_pk_bf16_f32 v230, v122, v123
	v_cvt_pk_bf16_f32 v231, v124, v125
	v_cvt_pk_bf16_f32 v232, v114, v115
	v_cvt_pk_bf16_f32 v233, v116, v117
	global_store_dwordx4 v[200:201], v[230:233], off
	v_add_u32_e32 v221, 16, v164
	v_mad_i64_i32 v[202:203], s[12:13], v221, s80, v[160:161]
	v_pk_mul_f32 v[106:107], v[110:111], v[106:107]
	v_pk_mul_f32 v[108:109], v[112:113], v[108:109]
	v_pk_mul_f32 v[98:99], v[102:103], v[98:99]
	v_pk_mul_f32 v[100:101], v[104:105], v[100:101]
	v_pk_mul_f32 v[110:111], v[110:111], v[252:253]
	v_pk_mul_f32 v[112:113], v[112:113], v[252:253]
	v_pk_mul_f32 v[102:103], v[102:103], v[252:253]
	v_pk_mul_f32 v[104:105], v[104:105], v[252:253]
	v_exp_f32_e32 v110, v110
	v_exp_f32_e32 v111, v111
	v_exp_f32_e32 v112, v112
	v_exp_f32_e32 v113, v113
	v_exp_f32_e32 v102, v102
	v_exp_f32_e32 v103, v103
	v_exp_f32_e32 v104, v104
	v_exp_f32_e32 v105, v105
	v_pk_add_f32 v[110:111], v[110:111], v[250:251]
	v_pk_add_f32 v[112:113], v[112:113], v[250:251]
	v_pk_add_f32 v[102:103], v[102:103], v[250:251]
	v_pk_add_f32 v[104:105], v[104:105], v[250:251]
	v_rcp_f32_e32 v110, v110
	v_rcp_f32_e32 v111, v111
	v_rcp_f32_e32 v112, v112
	v_rcp_f32_e32 v113, v113
	v_rcp_f32_e32 v102, v102
	v_rcp_f32_e32 v103, v103
	v_rcp_f32_e32 v104, v104
	v_rcp_f32_e32 v105, v105
	v_pk_mul_f32 v[106:107], v[106:107], v[110:111]
	v_pk_mul_f32 v[108:109], v[108:109], v[112:113]
	v_pk_mul_f32 v[98:99], v[98:99], v[102:103]
	v_pk_mul_f32 v[100:101], v[100:101], v[104:105]
	v_cvt_pk_bf16_f32 v234, v106, v107
	v_cvt_pk_bf16_f32 v235, v108, v109
	v_cvt_pk_bf16_f32 v236, v98, v99
	v_cvt_pk_bf16_f32 v237, v100, v101
	global_store_dwordx4 v[202:203], v[234:237], off
	v_add_u32_e32 v222, 32, v164
	v_mad_i64_i32 v[204:205], s[12:13], v222, s80, v[160:161]
	v_pk_mul_f32 v[90:91], v[94:95], v[90:91]
	v_pk_mul_f32 v[92:93], v[96:97], v[92:93]
	v_pk_mul_f32 v[82:83], v[86:87], v[82:83]
	v_pk_mul_f32 v[84:85], v[88:89], v[84:85]
	v_pk_mul_f32 v[94:95], v[94:95], v[252:253]
	v_pk_mul_f32 v[96:97], v[96:97], v[252:253]
	v_pk_mul_f32 v[86:87], v[86:87], v[252:253]
	v_pk_mul_f32 v[88:89], v[88:89], v[252:253]
	v_exp_f32_e32 v94, v94
	v_exp_f32_e32 v95, v95
	v_exp_f32_e32 v96, v96
	v_exp_f32_e32 v97, v97
	v_exp_f32_e32 v86, v86
	v_exp_f32_e32 v87, v87
	v_exp_f32_e32 v88, v88
	v_exp_f32_e32 v89, v89
	v_pk_add_f32 v[94:95], v[94:95], v[250:251]
	v_pk_add_f32 v[96:97], v[96:97], v[250:251]
	v_pk_add_f32 v[86:87], v[86:87], v[250:251]
	v_pk_add_f32 v[88:89], v[88:89], v[250:251]
	v_rcp_f32_e32 v94, v94
	v_rcp_f32_e32 v95, v95
	v_rcp_f32_e32 v96, v96
	v_rcp_f32_e32 v97, v97
	v_rcp_f32_e32 v86, v86
	v_rcp_f32_e32 v87, v87
	v_rcp_f32_e32 v88, v88
	v_rcp_f32_e32 v89, v89
	v_pk_mul_f32 v[90:91], v[90:91], v[94:95]
	v_pk_mul_f32 v[92:93], v[92:93], v[96:97]
	v_pk_mul_f32 v[82:83], v[82:83], v[86:87]
	v_pk_mul_f32 v[84:85], v[84:85], v[88:89]
	v_cvt_pk_bf16_f32 v238, v90, v91
	v_cvt_pk_bf16_f32 v239, v92, v93
	v_cvt_pk_bf16_f32 v240, v82, v83
	v_cvt_pk_bf16_f32 v241, v84, v85
	global_store_dwordx4 v[204:205], v[238:241], off
	s_cmp_eq_u64 s[8:9], 0
	s_cbranch_scc1 .Lxl_skip
	s_barrier
; __device__ __forceinline__ u32x4 pack8(const float (&o)[8]) { u32x4 r; r.x = pk2(o[0], o[1]); r.y = pk2(o[2], o[3]); r.z = pk2(o[4], o[5]); r.w = pk2(o[6], o[7]); return r; }
; __device__ __forceinline__ float silu_f(float v) { return v * __builtin_amdgcn_rcpf(1.f + __expf(-v)); }
;     __device__ __forceinline__ void operator()(const f32x4 (&acc)[2][2][4][2], const pg8::Unit& u, int wr, int wc, int fr, int fq, int) const {
;         const int row0 = u.pm * 256 + wr * 64 + fr, col0 = u.pn * 128 + wc * 32 + 8 * fq;
; #pragma unroll
;         for (int ai = 0; ai < 2; ++ai)
; #pragma unroll
;             for (int m = 0; m < 4; ++m) { bf16_t* rowp = O + (size_t)(row0 + ai * 128 + m * 16) * DFF + col0;
;                 float r[8];
; #pragma unroll
;                 for (int n = 0; n < 2; ++n)
; #pragma unroll
;                     for (int i = 0; i < 4; ++i) { const float gt = acc[ai][0][m][n][i], up = acc[ai][1][m][n][i]; r[n * 4 + i] = silu_f(gt) * up; }
;                 *(u32x4*)rowp = pack8(r); }
.Lxl_skip:
	v_add_u32_e32 v223, 48, v164
	v_mad_i64_i32 v[206:207], s[12:13], v223, s80, v[160:161]
	v_pk_mul_f32 v[74:75], v[78:79], v[74:75]
	v_pk_mul_f32 v[76:77], v[80:81], v[76:77]
	v_pk_mul_f32 v[66:67], v[70:71], v[66:67]
	v_pk_mul_f32 v[68:69], v[72:73], v[68:69]
	v_pk_mul_f32 v[78:79], v[78:79], v[252:253]
	v_pk_mul_f32 v[80:81], v[80:81], v[252:253]
	v_pk_mul_f32 v[70:71], v[70:71], v[252:253]
	v_pk_mul_f32 v[72:73], v[72:73], v[252:253]
	v_exp_f32_e32 v78, v78
	v_exp_f32_e32 v79, v79
	v_exp_f32_e32 v80, v80
	v_exp_f32_e32 v81, v81
	v_exp_f32_e32 v70, v70
	v_exp_f32_e32 v71, v71
	v_exp_f32_e32 v72, v72
	v_exp_f32_e32 v73, v73
	v_pk_add_f32 v[78:79], v[78:79], v[250:251]
	v_pk_add_f32 v[80:81], v[80:81], v[250:251]
	v_pk_add_f32 v[70:71], v[70:71], v[250:251]
	v_pk_add_f32 v[72:73], v[72:73], v[250:251]
	v_rcp_f32_e32 v78, v78
	v_rcp_f32_e32 v79, v79
	v_rcp_f32_e32 v80, v80
	v_rcp_f32_e32 v81, v81
	v_rcp_f32_e32 v70, v70
	v_rcp_f32_e32 v71, v71
	v_rcp_f32_e32 v72, v72
	v_rcp_f32_e32 v73, v73
	v_pk_mul_f32 v[74:75], v[74:75], v[78:79]
	v_pk_mul_f32 v[76:77], v[76:77], v[80:81]
	v_pk_mul_f32 v[66:67], v[66:67], v[70:71]
	v_pk_mul_f32 v[68:69], v[68:69], v[72:73]
	v_cvt_pk_bf16_f32 v242, v74, v75
	v_cvt_pk_bf16_f32 v243, v76, v77
	v_cvt_pk_bf16_f32 v244, v66, v67
	v_cvt_pk_bf16_f32 v245, v68, v69
	global_store_dwordx4 v[206:207], v[242:245], off
	v_add_u32_e32 v224, 128, v164
	v_mad_i64_i32 v[208:209], s[12:13], v224, s80, v[160:161]
	v_pk_mul_f32 v[58:59], v[62:63], v[58:59]
	v_pk_mul_f32 v[60:61], v[64:65], v[60:61]
	v_pk_mul_f32 v[50:51], v[54:55], v[50:51]
	v_pk_mul_f32 v[52:53], v[56:57], v[52:53]
	v_pk_mul_f32 v[62:63], v[62:63], v[252:253]
	v_pk_mul_f32 v[64:65], v[64:65], v[252:253]
	v_pk_mul_f32 v[54:55], v[54:55], v[252:253]
	v_pk_mul_f32 v[56:57], v[56:57], v[252:253]
	v_exp_f32_e32 v62, v62
	v_exp_f32_e32 v63, v63
	v_exp_f32_e32 v64, v64
	v_exp_f32_e32 v65, v65
	v_exp_f32_e32 v54, v54
	v_exp_f32_e32 v55, v55
	v_exp_f32_e32 v56, v56
	v_exp_f32_e32 v57, v57
	v_pk_add_f32 v[62:63], v[62:63], v[250:251]
	v_pk_add_f32 v[64:65], v[64:65], v[250:251]
	v_pk_add_f32 v[54:55], v[54:55], v[250:251]
	v_pk_add_f32 v[56:57], v[56:57], v[250:251]
	v_rcp_f32_e32 v62, v62
	v_rcp_f32_e32 v63, v63
	v_rcp_f32_e32 v64, v64
	v_rcp_f32_e32 v65, v65
	v_rcp_f32_e32 v54, v54
	v_rcp_f32_e32 v55, v55
	v_rcp_f32_e32 v56, v56
	v_rcp_f32_e32 v57, v57
	v_pk_mul_f32 v[58:59], v[58:59], v[62:63]
	v_pk_mul_f32 v[60:61], v[60:61], v[64:65]
	v_pk_mul_f32 v[50:51], v[50:51], v[54:55]
	v_pk_mul_f32 v[52:53], v[52:53], v[56:57]
	v_cvt_pk_bf16_f32 v230, v58, v59
	v_cvt_pk_bf16_f32 v231, v60, v61
	v_cvt_pk_bf16_f32 v232, v50, v51
	v_cvt_pk_bf16_f32 v233, v52, v53
	global_store_dwordx4 v[208:209], v[230:233], off
	v_add_u32_e32 v225, 144, v164
	v_mad_i64_i32 v[210:211], s[12:13], v225, s80, v[160:161]
	v_pk_mul_f32 v[42:43], v[46:47], v[42:43]
	v_pk_mul_f32 v[44:45], v[48:49], v[44:45]
	v_pk_mul_f32 v[34:35], v[38:39], v[34:35]
	v_pk_mul_f32 v[36:37], v[40:41], v[36:37]
	v_pk_mul_f32 v[46:47], v[46:47], v[252:253]
	v_pk_mul_f32 v[48:49], v[48:49], v[252:253]
	v_pk_mul_f32 v[38:39], v[38:39], v[252:253]
	v_pk_mul_f32 v[40:41], v[40:41], v[252:253]
	v_exp_f32_e32 v46, v46
	v_exp_f32_e32 v47, v47
	v_exp_f32_e32 v48, v48
	v_exp_f32_e32 v49, v49
	v_exp_f32_e32 v38, v38
	v_exp_f32_e32 v39, v39
	v_exp_f32_e32 v40, v40
	v_exp_f32_e32 v41, v41
	v_pk_add_f32 v[46:47], v[46:47], v[250:251]
	v_pk_add_f32 v[48:49], v[48:49], v[250:251]
	v_pk_add_f32 v[38:39], v[38:39], v[250:251]
	v_pk_add_f32 v[40:41], v[40:41], v[250:251]
	v_rcp_f32_e32 v46, v46
	v_rcp_f32_e32 v47, v47
	v_rcp_f32_e32 v48, v48
	v_rcp_f32_e32 v49, v49
	v_rcp_f32_e32 v38, v38
	v_rcp_f32_e32 v39, v39
	v_rcp_f32_e32 v40, v40
	v_rcp_f32_e32 v41, v41
	v_pk_mul_f32 v[42:43], v[42:43], v[46:47]
	v_pk_mul_f32 v[44:45], v[44:45], v[48:49]
	v_pk_mul_f32 v[34:35], v[34:35], v[38:39]
	v_pk_mul_f32 v[36:37], v[36:37], v[40:41]
	v_cvt_pk_bf16_f32 v234, v42, v43
	v_cvt_pk_bf16_f32 v235, v44, v45
	v_cvt_pk_bf16_f32 v236, v34, v35
	v_cvt_pk_bf16_f32 v237, v36, v37
	global_store_dwordx4 v[210:211], v[234:237], off
	v_add_u32_e32 v226, 160, v164
	v_mad_i64_i32 v[212:213], s[12:13], v226, s80, v[160:161]
	v_pk_mul_f32 v[26:27], v[30:31], v[26:27]
	v_pk_mul_f32 v[28:29], v[32:33], v[28:29]
	v_pk_mul_f32 v[18:19], v[22:23], v[18:19]
	v_pk_mul_f32 v[20:21], v[24:25], v[20:21]
	v_pk_mul_f32 v[30:31], v[30:31], v[252:253]
	v_pk_mul_f32 v[32:33], v[32:33], v[252:253]
	v_pk_mul_f32 v[22:23], v[22:23], v[252:253]
	v_pk_mul_f32 v[24:25], v[24:25], v[252:253]
	v_exp_f32_e32 v30, v30
	v_exp_f32_e32 v31, v31
	v_exp_f32_e32 v32, v32
	v_exp_f32_e32 v33, v33
	v_exp_f32_e32 v22, v22
	v_exp_f32_e32 v23, v23
	v_exp_f32_e32 v24, v24
	v_exp_f32_e32 v25, v25
	v_pk_add_f32 v[30:31], v[30:31], v[250:251]
	v_pk_add_f32 v[32:33], v[32:33], v[250:251]
	v_pk_add_f32 v[22:23], v[22:23], v[250:251]
	v_pk_add_f32 v[24:25], v[24:25], v[250:251]
	v_rcp_f32_e32 v30, v30
	v_rcp_f32_e32 v31, v31
	v_rcp_f32_e32 v32, v32
	v_rcp_f32_e32 v33, v33
	v_rcp_f32_e32 v22, v22
	v_rcp_f32_e32 v23, v23
	v_rcp_f32_e32 v24, v24
	v_rcp_f32_e32 v25, v25
	v_pk_mul_f32 v[26:27], v[26:27], v[30:31]
	v_pk_mul_f32 v[28:29], v[28:29], v[32:33]
	v_pk_mul_f32 v[18:19], v[18:19], v[22:23]
	v_pk_mul_f32 v[20:21], v[20:21], v[24:25]
	v_cvt_pk_bf16_f32 v238, v26, v27
	v_cvt_pk_bf16_f32 v239, v28, v29
	v_cvt_pk_bf16_f32 v240, v18, v19
	v_cvt_pk_bf16_f32 v241, v20, v21
	global_store_dwordx4 v[212:213], v[238:241], off
	v_add_u32_e32 v227, 176, v164
	v_mad_i64_i32 v[214:215], s[12:13], v227, s80, v[160:161]
	v_pk_mul_f32 v[10:11], v[14:15], v[10:11]
	v_pk_mul_f32 v[12:13], v[16:17], v[12:13]
	v_pk_mul_f32 v[2:3], v[6:7], v[2:3]
	v_pk_mul_f32 v[4:5], v[8:9], v[4:5]
	v_pk_mul_f32 v[14:15], v[14:15], v[252:253]
	v_pk_mul_f32 v[16:17], v[16:17], v[252:253]
	v_pk_mul_f32 v[6:7], v[6:7], v[252:253]
	v_pk_mul_f32 v[8:9], v[8:9], v[252:253]
	v_exp_f32_e32 v14, v14
	v_exp_f32_e32 v15, v15
	v_exp_f32_e32 v16, v16
	v_exp_f32_e32 v17, v17
	v_exp_f32_e32 v6, v6
	v_exp_f32_e32 v7, v7
	v_exp_f32_e32 v8, v8
	v_exp_f32_e32 v9, v9
	v_pk_add_f32 v[14:15], v[14:15], v[250:251]
	v_pk_add_f32 v[16:17], v[16:17], v[250:251]
	v_pk_add_f32 v[6:7], v[6:7], v[250:251]
	v_pk_add_f32 v[8:9], v[8:9], v[250:251]
	v_rcp_f32_e32 v14, v14
	v_rcp_f32_e32 v15, v15
	v_rcp_f32_e32 v16, v16
	v_rcp_f32_e32 v17, v17
	v_rcp_f32_e32 v6, v6
	v_rcp_f32_e32 v7, v7
	v_rcp_f32_e32 v8, v8
	v_rcp_f32_e32 v9, v9
	v_pk_mul_f32 v[10:11], v[10:11], v[14:15]
	v_pk_mul_f32 v[12:13], v[12:13], v[16:17]
	v_pk_mul_f32 v[2:3], v[2:3], v[6:7]
	v_pk_mul_f32 v[4:5], v[4:5], v[8:9]
	v_cvt_pk_bf16_f32 v242, v10, v11
	v_cvt_pk_bf16_f32 v243, v12, v13
	v_cvt_pk_bf16_f32 v244, v2, v3
	v_cvt_pk_bf16_f32 v245, v4, v5
	global_store_dwordx4 v[214:215], v[242:245], off
	s_mov_b64 s[12:13], -1
	s_cbranch_vccnz .LBB0_1042
	s_branch .LBB0_1041
